# sample attention stagger: 8 phases an eighth of a tile apart by (blockIdx>>3)&7 (within-XCD)
# speedup vs baseline: 1.0374x; 1.0009x over previous
.LBB0_779:
	s_lshr_b32 s0, s14, 3
	s_and_b32 s0, s0, 7
.Lsa_stagger:
	s_cmp_eq_u32 s0, 0
	s_cbranch_scc1 .Lsa_stagger_done
	s_sleep 22
	s_sub_u32 s0, s0, 1
	s_branch .Lsa_stagger
